# v47: v44 + FoX K/V register prefetch two tiles deep (loop unrolled x2, two register sets, counted vmcnt)
# speedup vs baseline: 1.0018x; 1.0018x over previous
; DI void fox_attn(const Params& P, int bh, int qb, unsigned char* smem, int tt) {
;     ...
;     rk0 = *(const u32x4*)kg; rk1 = *(const u32x4*)(kg + 32 * 1024);
;     rv0 = *(const u32x4*)vg; rv1 = *(const u32x4*)(vg + 32 * TSEQ);
;     if (tid < 64) rc = cf[tid] * L2E;
;     {
;         bf16_t* Ks = (bf16_t*)smem; bf16_t* VTs = Ks + 64 * 72; float* cks = (float*)(smem + 2 * 64 * 72 * 2);
;         *(u32x4*)(Ks + srow * 72 + scol) = rk0; *(u32x4*)(Ks + (srow + 32) * 72 + scol) = rk1;
;         *(u32x4*)(VTs + srow * 72 + scol) = rv0; *(u32x4*)(VTs + (srow + 32) * 72 + scol) = rv1;
;         if (tid < 64) cks[tid] = rc;
;     }
;     __syncthreads();
; #pragma unroll 1
;     for (int kt = 0; kt < ntiles; ++kt) {
;         const unsigned char* bufc = smem + (kt & 1) * BUFB;
;         const bf16_t* Ks = (const bf16_t*)bufc; const bf16_t* VTs = Ks + 64 * 72; const float* cks = (const float*)(bufc + 2 * 64 * 72 * 2);
;         const bool more = kt + 1 < ntiles;
;         if (more) {
;             const bf16_t* kg2 = kg + (size_t)(kt + 1) * 64 * 1024; const bf16_t* vg2 = vg + (kt + 1) * 64;
;             rk0 = *(const u32x4*)kg2; rk1 = *(const u32x4*)(kg2 + 32 * 1024);
;             rv0 = *(const u32x4*)vg2; rv1 = *(const u32x4*)(vg2 + 32 * TSEQ);
;             if (tid < 64) rc = cf[(kt + 1) * 64 + tid] * L2E;
.LBB0_542:
	s_or_b64 exec, exec, s[2:3]
	v_mul_u32_u24_e32 v0, 0x48, v2
	v_lshlrev_b32_e32 v119, 1, v0
	v_add3_u32 v0, v131, v119, v104
	s_waitcnt vmcnt(4)
	ds_write_b128 v0, v[82:85]
	s_waitcnt vmcnt(3)
	ds_write_b128 v0, v[86:89] offset:4608
	s_waitcnt vmcnt(1)
	ds_write_b128 v0, v[90:93] offset:9216
	s_waitcnt vmcnt(0)
	ds_write_b128 v0, v[94:97] offset:13824
	s_and_saveexec_b64 s[2:3], s[0:1]
	v_lshl_add_u32 v0, v130, 2, v131
	ds_write_b32 v0, v118 offset:18432
	s_or_b64 exec, exec, s[2:3]
	v_lshlrev_b32_e32 v0, 3, v23
	v_mul_f32_e32 v121, 0x3fb8aa3b, v3
	v_lshlrev_b32_e32 v105, 2, v23
	v_lshlrev_b32_e32 v3, 2, v14
	v_lshl_add_u32 v125, v0, 1, v131
	v_sub_u32_e32 v126, 0, v0
	v_add_u32_e32 v0, v9, v22
	v_xor_b32_e32 v99, 0x80, v3
	v_sub_u32_e32 v0, v0, v105
	v_lshlrev_b32_e32 v3, 7, v8
	v_sub_u32_e32 v0, v0, v3
	v_lshlrev_b64 v[4:5], 22, v[4:5]
	v_add_u32_e32 v127, 0x780, v0
	v_lshl_or_b32 v0, v2, 11, v4
	v_lshlrev_b32_e32 v2, 1, v12
	v_and_b32_e32 v3, 7, v10
	v_and_b32_e32 v2, 0x380, v2
	v_lshlrev_b32_e32 v3, 4, v3
	v_or3_b32 v4, v0, v2, v3
	v_mov_b32_e32 v14, v1
	v_mov_b32_e32 v15, v1
	v_lshlrev_b64 v[100:101], 10, v[6:7]
	v_lshlrev_b32_e32 v122, 1, v11
	v_mul_u32_u24_e32 v124, 0x48, v22
	v_lshl_add_u64 v[108:109], s[10:11], 0, v[4:5]
	v_mov_b32_e32 v0, v1
	v_mov_b32_e32 v2, v1
	v_mov_b32_e32 v3, v1
	v_mov_b32_e32 v4, v1
	v_mov_b32_e32 v5, v1
	v_mov_b32_e32 v6, v1
	v_mov_b32_e32 v7, v1
	v_mov_b32_e32 v8, v1
	v_mov_b32_e32 v9, v1
	v_mov_b32_e32 v10, v1
	v_mov_b32_e32 v11, v1
	v_mov_b32_e32 v12, v1
	v_mov_b32_e32 v13, v1
	v_mov_b64_e32 v[32:33], v[14:15]
	v_mov_b64_e32 v[30:31], v[12:13]
	v_mov_b64_e32 v[28:29], v[10:11]
	v_mov_b64_e32 v[26:27], v[8:9]
	v_mov_b64_e32 v[24:25], v[6:7]
	v_mov_b64_e32 v[22:23], v[4:5]
	v_mov_b64_e32 v[20:21], v[2:3]
	v_mov_b64_e32 v[18:19], v[0:1]
	v_mov_b64_e32 v[16:17], v[14:15]
	v_add_u32_e32 v123, 2, v122
	s_mov_b32 s47, 0
	v_mov_b32_e32 v120, 0
	v_mov_b32_e32 v128, 0xf149f2ca
	s_mov_b32 s34, 64
	s_mov_b64 s[30:31], 0
	v_mov_b64_e32 v[14:15], v[12:13]
	v_mov_b64_e32 v[12:13], v[10:11]
	v_mov_b64_e32 v[10:11], v[8:9]
	v_mov_b64_e32 v[8:9], v[6:7]
	v_mov_b64_e32 v[6:7], v[4:5]
	v_mov_b64_e32 v[4:5], v[2:3]
	v_mov_b64_e32 v[2:3], v[0:1]
	s_waitcnt lgkmcnt(0)
	s_mov_b32 s35, s14
	v_add_co_u32_e32 v36, vcc, 0xffff0000, v108
	v_lshl_add_u64 v[34:35], s[34:35], 1, v[106:107]
	s_nop 0
	v_addc_co_u32_e32 v37, vcc, -1, v109, vcc
	global_load_dwordx4 v[82:85], v[36:37], off
	global_load_dwordx4 v[86:89], v[108:109], off
	global_load_dwordx4 v[90:93], v[34:35], off
	v_add_co_u32_e32 v34, vcc, 0x20000, v34
	s_nop 1
	v_addc_co_u32_e32 v35, vcc, 0, v35, vcc
	global_load_dwordx4 v[94:97], v[34:35], off
	v_add_u32_e32 v0, s34, v130
	v_lshl_add_u64 v[34:35], v[0:1], 2, v[102:103]
	global_load_dword v118, v[34:35], off
	s_add_i32 s34, s34, 64
	v_lshl_add_u64 v[108:109], v[108:109], 0, s[18:19]
	s_barrier
	s_branch .LBB0_546

; DI void fox_attn(const Params& P, int bh, int qb, unsigned char* smem, int tt) {
;     ...
;     for (int kt = 0; kt < ntiles; ++kt) {
;         const unsigned char* bufc = smem + (kt & 1) * BUFB;
;         const bf16_t* Ks = (const bf16_t*)bufc; const bf16_t* VTs = Ks + 64 * 72; const float* cks = (const float*)(bufc + 2 * 64 * 72 * 2);
;         const bool more = kt + 1 < ntiles;
;         if (more) {
;             const bf16_t* kg2 = kg + (size_t)(kt + 1) * 64 * 1024; const bf16_t* vg2 = vg + (kt + 1) * 64;
;             rk0 = *(const u32x4*)kg2; rk1 = *(const u32x4*)(kg2 + 32 * 1024);
;             rv0 = *(const u32x4*)vg2; rv1 = *(const u32x4*)(vg2 + 32 * TSEQ);
;             if (tid < 64) rc = cf[(kt + 1) * 64 + tid] * L2E;
;         }
.LBB0_546:
	s_mov_b32 s56, s47
	s_add_i32 s47, s47, 1
	v_cmp_lt_u32_e64 s[2:3], s47, v123
	s_add_i32 s64, s47, 1
	v_cmp_lt_u32_e64 s[66:67], s64, v123
	s_and_saveexec_b64 s[36:37], s[66:67]
	s_cbranch_execz .LBB0_550
	s_mov_b32 s35, s14
	v_add_co_u32_e32 v36, vcc, 0xffff0000, v108
	v_lshl_add_u64 v[34:35], s[34:35], 1, v[106:107]
	s_nop 0
	v_addc_co_u32_e32 v37, vcc, -1, v109, vcc
	global_load_dwordx4 v[186:189], v[36:37], off
	global_load_dwordx4 v[190:193], v[108:109], off
	global_load_dwordx4 v[194:197], v[34:35], off
	v_add_co_u32_e32 v34, vcc, 0x20000, v34
	s_nop 1
	v_addc_co_u32_e32 v35, vcc, 0, v35, vcc
	global_load_dwordx4 v[198:201], v[34:35], off
	v_add_u32_e32 v0, s34, v130
	v_lshl_add_u64 v[34:35], v[0:1], 2, v[102:103]
	global_load_dword v202, v[34:35], off

; DI void fox_attn(const Params& P, int bh, int qb, unsigned char* smem, int tt) {
;     ...
;         {
;             const float sh = cq - m;
;             const f32x2v sh2 = {sh, sh};
;             f32x2v rs2 = {0.f, 0.f};
; #pragma unroll
;             for (int mt = 0; mt < 2; ++mt)
; #pragma unroll
;                 for (int p2 = 0; p2 < 8; ++p2) {
;                     const f32x2v sv = {sacc[mt][2 * p2], sacc[mt][2 * p2 + 1]};
;                     const f32x2v t = sv + sh2;
;                     f32x2v pp; pp.x = __builtin_amdgcn_exp2f(t.x); pp.y = __builtin_amdgcn_exp2f(t.y);
;                     sacc[mt][2 * p2] = pp.x; sacc[mt][2 * p2 + 1] = pp.y;
;                     rs2 = rs2 + pp;
;                 }
;             l += rs2.x + rs2.y;
;         }
;         {
;             u32x4 vw[2][2][2];
; #pragma unroll
;             for (int mt = 0; mt < 2; ++mt)
; #pragma unroll
;                 for (int s = 0; s < 2; ++s)
; #pragma unroll
;                     for (int dt = 0; dt < 2; ++dt) {
;                         const bf16_t* vp = VTs + (dt * 32 + r) * 72 + mt * 32 + 16 * s + 4 * h2;
;                         const u32x2 lo = *(const u32x2*)vp, hi = *(const u32x2*)(vp + 8);
;                         vw[mt][s][dt].x = lo.x; vw[mt][s][dt].y = lo.y; vw[mt][s][dt].z = hi.x; vw[mt][s][dt].w = hi.y;
;                     }
;             u32x4 pw[2][2];
; #pragma unroll
;             for (int mt = 0; mt < 2; ++mt)
; #pragma unroll
;                 for (int s = 0; s < 2; ++s) {
;                     pw[mt][s].x = pack2(sacc[mt][8 * s + 0], sacc[mt][8 * s + 1]); pw[mt][s].y = pack2(sacc[mt][8 * s + 2], sacc[mt][8 * s + 3]);
;                     pw[mt][s].z = pack2(sacc[mt][8 * s + 4], sacc[mt][8 * s + 5]); pw[mt][s].w = pack2(sacc[mt][8 * s + 6], sacc[mt][8 * s + 7]);
;                 }
;             __builtin_amdgcn_sched_barrier(0);
; #pragma unroll
;             for (int mt = 0; mt < 2; ++mt)
; #pragma unroll
;                 for (int s = 0; s < 2; ++s) {
;                     const bf16x8 pf = __builtin_bit_cast(bf16x8, pw[mt][s]);
;                     O[0] = MFMA32(__builtin_bit_cast(bf16x8, vw[mt][s][0]), pf, O[0]);
;                     O[1] = MFMA32(__builtin_bit_cast(bf16x8, vw[mt][s][1]), pf, O[1]);
;                 }
;         }
;         if (more) {
;             unsigned char* bufn = smem + ((kt + 1) & 1) * BUFB;
.LBB0_554:
	v_sub_f32_e32 v132, v121, v128
	v_pk_add_f32 v[44:45], v[110:111], v[132:133] op_sel_hi:[1,0]
	v_lshlrev_b32_e32 v110, 1, v124
	v_add3_u32 v0, v0, v126, v110
	v_add_u32_e32 v129, 0x2000, v0
	v_add_u32_e32 v0, 0x3000, v0
	v_pk_add_f32 v[46:47], v[50:51], v[132:133] op_sel_hi:[1,0]
	v_pk_add_f32 v[48:49], v[114:115], v[132:133] op_sel_hi:[1,0]
	v_pk_add_f32 v[50:51], v[54:55], v[132:133] op_sel_hi:[1,0]
	v_pk_add_f32 v[54:55], v[112:113], v[132:133] op_sel_hi:[1,0]
	v_pk_add_f32 v[58:59], v[58:59], v[132:133] op_sel_hi:[1,0]
	v_pk_add_f32 v[64:65], v[116:117], v[132:133] op_sel_hi:[1,0]
	v_pk_add_f32 v[56:57], v[56:57], v[132:133] op_sel_hi:[1,0]
	v_pk_add_f32 v[62:63], v[62:63], v[132:133] op_sel_hi:[1,0]
	v_pk_add_f32 v[52:53], v[52:53], v[132:133] op_sel_hi:[1,0]
	v_pk_add_f32 v[60:61], v[60:61], v[132:133] op_sel_hi:[1,0]
	v_pk_add_f32 v[38:39], v[38:39], v[132:133] op_sel_hi:[1,0]
	v_pk_add_f32 v[42:43], v[42:43], v[132:133] op_sel_hi:[1,0]
	v_pk_add_f32 v[36:37], v[36:37], v[132:133] op_sel_hi:[1,0]
	v_pk_add_f32 v[40:41], v[40:41], v[132:133] op_sel_hi:[1,0]
	v_pk_add_f32 v[34:35], v[34:35], v[132:133] op_sel_hi:[1,0]
	ds_read2_b64 v[110:113], v129 offset0:128 offset1:130
	ds_read2_b64 v[114:117], v129 offset0:132 offset1:134
	ds_read2_b64 v[132:135], v0 offset0:192 offset1:194
	ds_read2_b64 v[136:139], v0 offset0:196 offset1:198
	ds_read2_b64 v[140:143], v129 offset0:136 offset1:138
	ds_read2_b64 v[144:147], v0 offset0:200 offset1:202
	ds_read2_b64 v[148:151], v129 offset0:140 offset1:142
	ds_read2_b64 v[152:155], v0 offset0:204 offset1:206
	v_exp_f32_e32 v44, v44
	v_exp_f32_e32 v45, v45
	v_exp_f32_e32 v46, v46
	v_exp_f32_e32 v47, v47
	v_exp_f32_e32 v48, v48
	v_exp_f32_e32 v49, v49
	v_exp_f32_e32 v50, v50
	v_exp_f32_e32 v51, v51
	v_exp_f32_e32 v54, v54
	v_exp_f32_e32 v55, v55
	v_exp_f32_e32 v58, v58
	v_exp_f32_e32 v59, v59
	v_exp_f32_e32 v64, v64
	v_exp_f32_e32 v65, v65
	v_exp_f32_e32 v56, v56
	v_exp_f32_e32 v57, v57
	v_exp_f32_e32 v62, v62
	v_exp_f32_e32 v63, v63
	v_exp_f32_e32 v52, v52
	v_exp_f32_e32 v53, v53
	v_exp_f32_e32 v60, v60
	v_exp_f32_e32 v61, v61
	v_exp_f32_e32 v38, v38
	v_exp_f32_e32 v39, v39
	v_exp_f32_e32 v42, v42
	v_exp_f32_e32 v43, v43
	v_exp_f32_e32 v36, v36
	v_exp_f32_e32 v37, v37
	v_exp_f32_e32 v40, v40
	v_exp_f32_e32 v41, v41
	v_exp_f32_e32 v34, v34
	v_exp_f32_e32 v35, v35
	v_cvt_pk_bf16_f32 v156, v44, v45
	v_cvt_pk_bf16_f32 v157, v46, v47
	v_cvt_pk_bf16_f32 v158, v48, v49
	v_cvt_pk_bf16_f32 v159, v50, v51
	v_cvt_pk_bf16_f32 v160, v54, v55
	v_cvt_pk_bf16_f32 v161, v58, v59
	v_cvt_pk_bf16_f32 v162, v64, v65
	v_cvt_pk_bf16_f32 v163, v56, v57
	v_cvt_pk_bf16_f32 v170, v62, v63
	v_cvt_pk_bf16_f32 v171, v52, v53
	v_cvt_pk_bf16_f32 v172, v60, v61
	v_cvt_pk_bf16_f32 v173, v38, v39
	v_cvt_pk_bf16_f32 v174, v42, v43
	v_cvt_pk_bf16_f32 v175, v36, v37
	v_cvt_pk_bf16_f32 v176, v40, v41
	v_cvt_pk_bf16_f32 v177, v34, v35
	s_waitcnt lgkmcnt(7)
	v_mfma_f32_32x32x16_bf16 v[18:33], v[110:113], v[156:159], v[18:33]
	s_waitcnt lgkmcnt(5)
	v_mfma_f32_32x32x16_bf16 v[2:17], v[132:135], v[156:159], v[2:17]
	v_mfma_f32_32x32x16_bf16 v[18:33], v[114:117], v[160:163], v[18:33]
	s_waitcnt lgkmcnt(4)
	v_mfma_f32_32x32x16_bf16 v[2:17], v[136:139], v[160:163], v[2:17]
	s_waitcnt lgkmcnt(3)
	v_mfma_f32_32x32x16_bf16 v[18:33], v[140:143], v[170:173], v[18:33]
	s_waitcnt lgkmcnt(2)
	v_mfma_f32_32x32x16_bf16 v[2:17], v[144:147], v[170:173], v[2:17]
	s_waitcnt lgkmcnt(1)
	v_mfma_f32_32x32x16_bf16 v[18:33], v[148:151], v[174:177], v[18:33]
	s_waitcnt lgkmcnt(0)
	v_mfma_f32_32x32x16_bf16 v[2:17], v[152:155], v[174:177], v[2:17]
	s_and_saveexec_b64 s[36:37], s[2:3]
	s_cbranch_execz .Lfx_tailE
	s_bitcmp1_b32 s47, 0
	s_cselect_b32 s2, 0x4900, 0
	v_add_u32_e32 v0, s2, v131
	v_add3_u32 v110, v0, v119, v104
	s_cmp_eq_u64 s[66:67], 0
	s_cbranch_scc1 .Lfx_E_wlast
	s_waitcnt vmcnt(9)
	ds_write_b128 v110, v[82:85]
	s_waitcnt vmcnt(8)
	ds_write_b128 v110, v[86:89] offset:4608
	s_waitcnt vmcnt(7)
	ds_write_b128 v110, v[90:93] offset:9216
	s_waitcnt vmcnt(6)
	ds_write_b128 v110, v[94:97] offset:13824
	s_waitcnt vmcnt(5)
	s_branch .Lfx_E_wrc
.Lfx_E_wlast:
	s_waitcnt vmcnt(4)
	ds_write_b128 v110, v[82:85]
	s_waitcnt vmcnt(3)
	ds_write_b128 v110, v[86:89] offset:4608
	s_waitcnt vmcnt(2)
	ds_write_b128 v110, v[90:93] offset:9216
	s_waitcnt vmcnt(1)
	ds_write_b128 v110, v[94:97] offset:13824
	s_waitcnt vmcnt(0)
.Lfx_E_wrc:
	s_and_b64 exec, exec, s[0:1]
	s_cbranch_execz .Lfx_tailE
	v_mul_f32_e32 v118, 0x3fb8aa3b, v118
	v_lshl_add_u32 v0, v130, 2, v0
	ds_write_b32 v0, v118 offset:18432
	s_branch .Lfx_tailE

; DI void fox_attn(const Params& P, int bh, int qb, unsigned char* smem, int tt) {
;     ...
;     for (int kt = 0; kt < ntiles; ++kt) {
;         const unsigned char* bufc = smem + (kt & 1) * BUFB;
;         const bf16_t* Ks = (const bf16_t*)bufc; const bf16_t* VTs = Ks + 64 * 72; const float* cks = (const float*)(bufc + 2 * 64 * 72 * 2);
;         const bool more = kt + 1 < ntiles;
;         if (more) {
;             const bf16_t* kg2 = kg + (size_t)(kt + 1) * 64 * 1024; const bf16_t* vg2 = vg + (kt + 1) * 64;
;             rk0 = *(const u32x4*)kg2; rk1 = *(const u32x4*)(kg2 + 32 * 1024);
;             rv0 = *(const u32x4*)vg2; rv1 = *(const u32x4*)(vg2 + 32 * TSEQ);
;             if (tid < 64) rc = cf[(kt + 1) * 64 + tid] * L2E;
;         }
.Lfxo_546:
	s_mov_b32 s56, s47
	s_add_i32 s47, s47, 1
	v_cmp_lt_u32_e64 s[2:3], s47, v123
	s_and_saveexec_b64 s[36:37], s[2:3]
	s_cbranch_execz .Lfxo_550
	s_mov_b32 s35, s14
	v_add_co_u32_e32 v36, vcc, 0xffff0000, v108
	v_lshl_add_u64 v[34:35], s[34:35], 1, v[106:107]
	s_nop 0
	v_addc_co_u32_e32 v37, vcc, -1, v109, vcc
	global_load_dwordx4 v[82:85], v[36:37], off
	global_load_dwordx4 v[86:89], v[108:109], off
	global_load_dwordx4 v[90:93], v[34:35], off
	v_add_co_u32_e32 v34, vcc, 0x20000, v34
	s_nop 1
	v_addc_co_u32_e32 v35, vcc, 0, v35, vcc
	global_load_dwordx4 v[94:97], v[34:35], off
	v_add_u32_e32 v0, s34, v130
	v_lshl_add_u64 v[34:35], v[0:1], 2, v[102:103]
	global_load_dword v118, v[34:35], off

; DI void fox_attn(const Params& P, int bh, int qb, unsigned char* smem, int tt) {
;     ...
;         {
;             const float sh = cq - m;
;             const f32x2v sh2 = {sh, sh};
;             f32x2v rs2 = {0.f, 0.f};
; #pragma unroll
;             for (int mt = 0; mt < 2; ++mt)
; #pragma unroll
;                 for (int p2 = 0; p2 < 8; ++p2) {
;                     const f32x2v sv = {sacc[mt][2 * p2], sacc[mt][2 * p2 + 1]};
;                     const f32x2v t = sv + sh2;
;                     f32x2v pp; pp.x = __builtin_amdgcn_exp2f(t.x); pp.y = __builtin_amdgcn_exp2f(t.y);
;                     sacc[mt][2 * p2] = pp.x; sacc[mt][2 * p2 + 1] = pp.y;
;                     rs2 = rs2 + pp;
;                 }
;             l += rs2.x + rs2.y;
;         }
;         {
;             u32x4 vw[2][2][2];
; #pragma unroll
;             for (int mt = 0; mt < 2; ++mt)
; #pragma unroll
;                 for (int s = 0; s < 2; ++s)
; #pragma unroll
;                     for (int dt = 0; dt < 2; ++dt) {
;                         const bf16_t* vp = VTs + (dt * 32 + r) * 72 + mt * 32 + 16 * s + 4 * h2;
;                         const u32x2 lo = *(const u32x2*)vp, hi = *(const u32x2*)(vp + 8);
;                         vw[mt][s][dt].x = lo.x; vw[mt][s][dt].y = lo.y; vw[mt][s][dt].z = hi.x; vw[mt][s][dt].w = hi.y;
;                     }
;             u32x4 pw[2][2];
; #pragma unroll
;             for (int mt = 0; mt < 2; ++mt)
; #pragma unroll
;                 for (int s = 0; s < 2; ++s) {
;                     pw[mt][s].x = pack2(sacc[mt][8 * s + 0], sacc[mt][8 * s + 1]); pw[mt][s].y = pack2(sacc[mt][8 * s + 2], sacc[mt][8 * s + 3]);
;                     pw[mt][s].z = pack2(sacc[mt][8 * s + 4], sacc[mt][8 * s + 5]); pw[mt][s].w = pack2(sacc[mt][8 * s + 6], sacc[mt][8 * s + 7]);
;                 }
;             __builtin_amdgcn_sched_barrier(0);
; #pragma unroll
;             for (int mt = 0; mt < 2; ++mt)
; #pragma unroll
;                 for (int s = 0; s < 2; ++s) {
;                     const bf16x8 pf = __builtin_bit_cast(bf16x8, pw[mt][s]);
;                     O[0] = MFMA32(__builtin_bit_cast(bf16x8, vw[mt][s][0]), pf, O[0]);
;                     O[1] = MFMA32(__builtin_bit_cast(bf16x8, vw[mt][s][1]), pf, O[1]);
;                 }
;         }
;         if (more) {
;             unsigned char* bufn = smem + ((kt + 1) & 1) * BUFB;
.Lfxo_554:
	v_sub_f32_e32 v132, v121, v128
	v_pk_add_f32 v[44:45], v[110:111], v[132:133] op_sel_hi:[1,0]
	v_lshlrev_b32_e32 v110, 1, v124
	v_add3_u32 v0, v0, v126, v110
	v_add_u32_e32 v129, 0x2000, v0
	v_add_u32_e32 v0, 0x3000, v0
	v_pk_add_f32 v[46:47], v[50:51], v[132:133] op_sel_hi:[1,0]
	v_pk_add_f32 v[48:49], v[114:115], v[132:133] op_sel_hi:[1,0]
	v_pk_add_f32 v[50:51], v[54:55], v[132:133] op_sel_hi:[1,0]
	v_pk_add_f32 v[54:55], v[112:113], v[132:133] op_sel_hi:[1,0]
	v_pk_add_f32 v[58:59], v[58:59], v[132:133] op_sel_hi:[1,0]
	v_pk_add_f32 v[64:65], v[116:117], v[132:133] op_sel_hi:[1,0]
	v_pk_add_f32 v[56:57], v[56:57], v[132:133] op_sel_hi:[1,0]
	v_pk_add_f32 v[62:63], v[62:63], v[132:133] op_sel_hi:[1,0]
	v_pk_add_f32 v[52:53], v[52:53], v[132:133] op_sel_hi:[1,0]
	v_pk_add_f32 v[60:61], v[60:61], v[132:133] op_sel_hi:[1,0]
	v_pk_add_f32 v[38:39], v[38:39], v[132:133] op_sel_hi:[1,0]
	v_pk_add_f32 v[42:43], v[42:43], v[132:133] op_sel_hi:[1,0]
	v_pk_add_f32 v[36:37], v[36:37], v[132:133] op_sel_hi:[1,0]
	v_pk_add_f32 v[40:41], v[40:41], v[132:133] op_sel_hi:[1,0]
	v_pk_add_f32 v[34:35], v[34:35], v[132:133] op_sel_hi:[1,0]
	ds_read2_b64 v[110:113], v129 offset0:128 offset1:130
	ds_read2_b64 v[114:117], v129 offset0:132 offset1:134
	ds_read2_b64 v[132:135], v0 offset0:192 offset1:194
	ds_read2_b64 v[136:139], v0 offset0:196 offset1:198
	ds_read2_b64 v[140:143], v129 offset0:136 offset1:138
	ds_read2_b64 v[144:147], v0 offset0:200 offset1:202
	ds_read2_b64 v[148:151], v129 offset0:140 offset1:142
	ds_read2_b64 v[152:155], v0 offset0:204 offset1:206
	v_exp_f32_e32 v44, v44
	v_exp_f32_e32 v45, v45
	v_exp_f32_e32 v46, v46
	v_exp_f32_e32 v47, v47
	v_exp_f32_e32 v48, v48
	v_exp_f32_e32 v49, v49
	v_exp_f32_e32 v50, v50
	v_exp_f32_e32 v51, v51
	v_exp_f32_e32 v54, v54
	v_exp_f32_e32 v55, v55
	v_exp_f32_e32 v58, v58
	v_exp_f32_e32 v59, v59
	v_exp_f32_e32 v64, v64
	v_exp_f32_e32 v65, v65
	v_exp_f32_e32 v56, v56
	v_exp_f32_e32 v57, v57
	v_exp_f32_e32 v62, v62
	v_exp_f32_e32 v63, v63
	v_exp_f32_e32 v52, v52
	v_exp_f32_e32 v53, v53
	v_exp_f32_e32 v60, v60
	v_exp_f32_e32 v61, v61
	v_exp_f32_e32 v38, v38
	v_exp_f32_e32 v39, v39
	v_exp_f32_e32 v42, v42
	v_exp_f32_e32 v43, v43
	v_exp_f32_e32 v36, v36
	v_exp_f32_e32 v37, v37
	v_exp_f32_e32 v40, v40
	v_exp_f32_e32 v41, v41
	v_exp_f32_e32 v34, v34
	v_exp_f32_e32 v35, v35
	v_cvt_pk_bf16_f32 v156, v44, v45
	v_cvt_pk_bf16_f32 v157, v46, v47
	v_cvt_pk_bf16_f32 v158, v48, v49
	v_cvt_pk_bf16_f32 v159, v50, v51
	v_cvt_pk_bf16_f32 v160, v54, v55
	v_cvt_pk_bf16_f32 v161, v58, v59
	v_cvt_pk_bf16_f32 v162, v64, v65
	v_cvt_pk_bf16_f32 v163, v56, v57
	v_cvt_pk_bf16_f32 v170, v62, v63
	v_cvt_pk_bf16_f32 v171, v52, v53
	v_cvt_pk_bf16_f32 v172, v60, v61
	v_cvt_pk_bf16_f32 v173, v38, v39
	v_cvt_pk_bf16_f32 v174, v42, v43
	v_cvt_pk_bf16_f32 v175, v36, v37
	v_cvt_pk_bf16_f32 v176, v40, v41
	v_cvt_pk_bf16_f32 v177, v34, v35
	s_waitcnt lgkmcnt(7)
	v_mfma_f32_32x32x16_bf16 v[18:33], v[110:113], v[156:159], v[18:33]
	s_waitcnt lgkmcnt(5)
	v_mfma_f32_32x32x16_bf16 v[2:17], v[132:135], v[156:159], v[2:17]
	v_mfma_f32_32x32x16_bf16 v[18:33], v[114:117], v[160:163], v[18:33]
	s_waitcnt lgkmcnt(4)
	v_mfma_f32_32x32x16_bf16 v[2:17], v[136:139], v[160:163], v[2:17]
	s_waitcnt lgkmcnt(3)
	v_mfma_f32_32x32x16_bf16 v[18:33], v[140:143], v[170:173], v[18:33]
	s_waitcnt lgkmcnt(2)
	v_mfma_f32_32x32x16_bf16 v[2:17], v[144:147], v[170:173], v[2:17]
	s_waitcnt lgkmcnt(1)
	v_mfma_f32_32x32x16_bf16 v[18:33], v[148:151], v[174:177], v[18:33]
	s_waitcnt lgkmcnt(0)
	v_mfma_f32_32x32x16_bf16 v[2:17], v[152:155], v[174:177], v[2:17]
	s_and_saveexec_b64 s[36:37], s[2:3]
	s_cbranch_execz .LBB0_545
	s_bitcmp1_b32 s47, 0
	s_cselect_b32 s2, 0x4900, 0
	v_add_u32_e32 v0, s2, v131
	v_add3_u32 v110, v0, v119, v104
	s_waitcnt vmcnt(9)
	ds_write_b128 v110, v[186:189]
	s_waitcnt vmcnt(8)
	ds_write_b128 v110, v[190:193] offset:4608
	s_waitcnt vmcnt(7)
	ds_write_b128 v110, v[194:197] offset:9216
	s_waitcnt vmcnt(6)
	ds_write_b128 v110, v[198:201] offset:13824
	s_waitcnt vmcnt(5)
	s_and_b64 exec, exec, s[0:1]
	s_cbranch_execz .LBB0_545
	v_mul_f32_e32 v202, 0x3fb8aa3b, v202
	v_lshl_add_u32 v0, v130, 2, v0
	ds_write_b32 v0, v202 offset:18432
	s_branch .LBB0_545
